# pass A part 1: wave reductions: zero-init + mov_dpp + add fused into add_dpp (row_bcast and first quad_perm steps)
# speedup vs baseline: 1.0245x; 1.0095x over previous
.LBB0_680:
	v_lshlrev_b32_e32 v0, 16, v75
	v_lshlrev_b32_e32 v96, 16, v37
	v_lshlrev_b32_e32 v94, 16, v39
	v_sub_f32_e32 v0, v0, v96
	v_sub_f32_e32 v1, v96, v94
	v_lshlrev_b32_e32 v92, 16, v46
	v_lshlrev_b32_e32 v2, 16, v48
	s_waitcnt vmcnt(9)
	v_fmac_f32_e32 v96, v84, v0
	v_sub_f32_e32 v0, v94, v92
	v_fmac_f32_e32 v94, v1, v84
	v_sub_f32_e32 v1, v92, v2
	v_lshlrev_b32_e32 v4, 16, v27
	v_lshlrev_b32_e32 v5, 16, v43
	v_fmac_f32_e32 v92, v0, v84
	v_fma_f32 v90, v1, v84, v2
	v_lshlrev_b32_e32 v1, 16, v38
	v_lshlrev_b32_e32 v0, 16, v76
	v_lshlrev_b32_e32 v7, 16, v50
	v_mov_b32_e32 v6, v1
	v_pk_add_f32 v[0:1], v[0:1], v[4:5] neg_lo:[0,1] neg_hi:[0,1]
	v_lshlrev_b32_e32 v11, 16, v42
	s_waitcnt vmcnt(8)
	v_pk_fma_f32 v[8:9], v[22:23], v[0:1], v[4:5] op_sel_hi:[0,1,1]
	v_lshlrev_b32_e32 v10, 16, v25
	v_pk_add_f32 v[4:5], v[4:5], v[6:7] neg_lo:[0,1] neg_hi:[0,1]
	v_lshlrev_b32_e32 v95, 16, v55
	v_lshlrev_b32_e32 v93, 16, v62
	v_pk_add_f32 v[0:1], v[10:11], -1.0 op_sel_hi:[1,0]
	v_pk_fma_f32 v[14:15], v[4:5], v[22:23], v[6:7] op_sel_hi:[1,0,1]
	v_sub_f32_e32 v2, v2, v95
	v_sub_f32_e32 v6, v95, v93
	v_lshlrev_b32_e32 v91, 16, v64
	v_lshlrev_b32_e32 v89, 16, v72
	s_waitcnt vmcnt(6)
	v_mul_f32_e32 v97, v85, v8
	s_waitcnt vmcnt(5)
	v_pk_fma_f32 v[0:1], v[0:1], v[26:27], 1.0 op_sel_hi:[1,0,0]
	v_lshlrev_b32_e32 v18, 16, v59
	v_fmac_f32_e32 v95, v2, v84
	v_sub_f32_e32 v2, v93, v91
	v_fmac_f32_e32 v93, v6, v84
	v_lshlrev_b32_e32 v19, 16, v70
	v_sub_f32_e32 v6, v91, v89
	v_lshlrev_b32_e32 v12, 16, v40
	v_lshlrev_b32_e32 v13, 16, v49
	v_mul_f32_e32 v29, v97, v97
	v_pk_mul_f32 v[0:1], v[8:9], v[0:1]
	v_mul_f32_e32 v98, v85, v14
	v_mul_f32_e32 v99, v85, v9
	v_lshlrev_b32_e32 v8, 16, v53
	v_lshlrev_b32_e32 v9, 16, v65
	v_fmac_f32_e32 v89, v6, v84
	v_pk_mov_b32 v[6:7], v[6:7], v[18:19] op_sel:[1,0]
	v_mov_b32_e32 v119, v3
	v_mul_f32_e32 v34, v98, v98
	v_pk_add_f32 v[4:5], v[12:13], -1.0 op_sel_hi:[1,0]
	v_pk_add_f32 v[6:7], v[6:7], v[8:9] neg_lo:[0,1] neg_hi:[0,1]
	v_mov_b32_dpp v119, v29 quad_perm:[1,0,3,2] row_mask:0xf bank_mask:0xf
	v_mov_b32_e32 v29, v3
	v_pk_fma_f32 v[4:5], v[4:5], v[26:27], 1.0 op_sel_hi:[1,0,0]
	v_mul_f32_e32 v102, v99, v99
	v_mul_f32_e32 v100, v85, v15
	v_pk_fma_f32 v[30:31], v[6:7], v[22:23], v[8:9] op_sel_hi:[1,0,1]
	v_pk_add_f32 v[8:9], v[8:9], v[18:19] neg_lo:[0,1] neg_hi:[0,1]
	v_mov_b32_dpp v29, v34 quad_perm:[1,0,3,2] row_mask:0xf bank_mask:0xf
	v_mov_b32_e32 v34, v3
	v_pk_mul_f32 v[4:5], v[14:15], v[4:5]
	v_mul_f32_e32 v106, v100, v100
	v_mul_f32_e32 v104, v85, v30
	v_lshlrev_b32_e32 v15, 16, v67
	v_lshlrev_b32_e32 v14, 16, v58
	v_pk_fma_f32 v[18:19], v[8:9], v[22:23], v[18:19] op_sel_hi:[1,0,1]
	v_mov_b32_dpp v34, v102 quad_perm:[1,0,3,2] row_mask:0xf bank_mask:0xf
	v_mov_b32_e32 v102, v3
	v_lshlrev_b32_e32 v16, 16, v60
	v_lshlrev_b32_e32 v17, 16, v73
	v_fmac_f32_e32 v91, v2, v84
	v_mul_f32_e32 v2, v104, v104
	v_pk_add_f32 v[6:7], v[14:15], -1.0 op_sel_hi:[1,0]
	v_mul_f32_e32 v110, v85, v18
	v_mov_b32_dpp v102, v106 quad_perm:[1,0,3,2] row_mask:0xf bank_mask:0xf
	v_mov_b32_e32 v106, v3
	v_pk_fma_f32 v[6:7], v[6:7], v[26:27], 1.0 op_sel_hi:[1,0,0]
	v_mul_f32_e32 v113, v110, v110
	v_pk_add_f32 v[8:9], v[16:17], -1.0 op_sel_hi:[1,0]
	v_mul_f32_e32 v111, v85, v31
	v_mov_b32_dpp v106, v2 quad_perm:[1,0,3,2] row_mask:0xf bank_mask:0xf
	v_mov_b32_e32 v2, v3
	v_pk_mul_f32 v[6:7], v[30:31], v[6:7]
	v_pk_fma_f32 v[8:9], v[8:9], v[26:27], 1.0 op_sel_hi:[1,0,0]
	v_mul_f32_e32 v31, v111, v111
	v_mul_f32_e32 v112, v85, v19
	v_mov_b32_dpp v2, v113 quad_perm:[1,0,3,2] row_mask:0xf bank_mask:0xf
	v_mov_b32_e32 v113, v3
	v_mul_f32_e32 v32, v96, v0
	v_pk_mul_f32 v[8:9], v[18:19], v[8:9]
	v_mul_f32_e32 v19, v112, v112
	v_mov_b32_dpp v113, v31 quad_perm:[1,0,3,2] row_mask:0xf bank_mask:0xf
	v_mov_b32_e32 v31, v3
	s_waitcnt vmcnt(4)
	v_mul_f32_e32 v33, v86, v32
	v_mul_f32_e32 v35, v94, v4
	v_mov_b32_dpp v31, v19 quad_perm:[1,0,3,2] row_mask:0xf bank_mask:0xf
	v_mul_f32_e32 v101, v86, v35
	v_mul_f32_e32 v30, v95, v6
	v_add_f32_dpp v19, v33, v33 quad_perm:[1,0,3,2] row_mask:0xf bank_mask:0xf
	v_mov_b32_e32 v32, v3
	v_mul_f32_e32 v109, v86, v30
	v_mul_f32_e32 v18, v93, v8
	v_mov_b32_dpp v32, v101 quad_perm:[1,0,3,2] row_mask:0xf bank_mask:0xf
	v_mul_f32_e32 v114, v86, v18
	v_mul_f32_e32 v115, v91, v7
	v_add_f32_dpp v101, v109, v109 quad_perm:[1,0,3,2] row_mask:0xf bank_mask:0xf
	v_mul_f32_e32 v116, v86, v115
	v_mul_f32_e32 v103, v92, v1
	v_add_f32_dpp v30, v114, v114 quad_perm:[1,0,3,2] row_mask:0xf bank_mask:0xf
	v_mul_f32_e32 v105, v86, v103
	v_fmac_f32_e32 v119, v97, v97
	v_mov_b32_e32 v33, v3
	v_add_f32_dpp v18, v116, v116 quad_perm:[1,0,3,2] row_mask:0xf bank_mask:0xf
	v_fmac_f32_e32 v29, v98, v98
	v_mov_b32_dpp v33, v105 quad_perm:[1,0,3,2] row_mask:0xf bank_mask:0xf
	v_add_f32_dpp v105, v119, v119 quad_perm:[2,3,0,1] row_mask:0xf bank_mask:0xf bound_ctrl:1
	v_add_f32_dpp v18, v18, v18 quad_perm:[2,3,0,1] row_mask:0xf bank_mask:0xf bound_ctrl:1
	v_add_f32_dpp v29, v29, v29 quad_perm:[2,3,0,1] row_mask:0xf bank_mask:0xf bound_ctrl:1
	v_add_f32_dpp v105, v105, v105 row_shr:4 row_mask:0xf bank_mask:0xf bound_ctrl:1
	v_add_f32_dpp v18, v18, v18 row_shr:4 row_mask:0xf bank_mask:0xf bound_ctrl:1
	v_mul_f32_e32 v107, v90, v5
	v_add_f32_dpp v105, v105, v105 row_shr:8 row_mask:0xf bank_mask:0xf bound_ctrl:1
	v_add_f32_dpp v116, v18, v18 row_shr:8 row_mask:0xf bank_mask:0xf bound_ctrl:1
	v_fmac_f32_e32 v34, v99, v99
	v_add_f32_dpp v29, v29, v29 row_shr:4 row_mask:0xf bank_mask:0xf bound_ctrl:1
	v_mul_f32_e32 v108, v86, v107
	v_fmac_f32_e32 v32, v86, v35
	v_add_f32_dpp v34, v34, v34 quad_perm:[2,3,0,1] row_mask:0xf bank_mask:0xf bound_ctrl:1
	v_add_f32_dpp v29, v29, v29 row_shr:8 row_mask:0xf bank_mask:0xf bound_ctrl:1
	v_add_f32_dpp v105, v105, v105 row_bcast:15 row_mask:0xa bank_mask:0xf
	v_fmac_f32_e32 v102, v100, v100
	v_fmac_f32_e32 v106, v104, v104
	v_fmac_f32_e32 v113, v111, v111
	v_add_f32_dpp v34, v34, v34 row_shr:4 row_mask:0xf bank_mask:0xf bound_ctrl:1
	v_add_f32_dpp v35, v108, v108 quad_perm:[1,0,3,2] row_mask:0xf bank_mask:0xf
	v_add_f32_dpp v102, v102, v102 quad_perm:[2,3,0,1] row_mask:0xf bank_mask:0xf bound_ctrl:1
	v_add_f32_dpp v106, v106, v106 quad_perm:[2,3,0,1] row_mask:0xf bank_mask:0xf bound_ctrl:1
	v_add_f32_dpp v107, v113, v113 quad_perm:[2,3,0,1] row_mask:0xf bank_mask:0xf bound_ctrl:1
	v_add_f32_dpp v34, v34, v34 row_shr:8 row_mask:0xf bank_mask:0xf bound_ctrl:1
	v_add_f32_dpp v113, v29, v29 row_bcast:15 row_mask:0xa bank_mask:0xf
	v_add_f32_dpp v102, v102, v102 row_shr:4 row_mask:0xf bank_mask:0xf bound_ctrl:1
	v_add_f32_dpp v106, v106, v106 row_shr:4 row_mask:0xf bank_mask:0xf bound_ctrl:1
	v_add_f32_dpp v101, v101, v101 quad_perm:[2,3,0,1] row_mask:0xf bank_mask:0xf bound_ctrl:1
	v_add_f32_dpp v102, v102, v102 row_shr:8 row_mask:0xf bank_mask:0xf bound_ctrl:1
	v_add_f32_dpp v108, v106, v106 row_shr:8 row_mask:0xf bank_mask:0xf bound_ctrl:1
	v_add_f32_dpp v106, v34, v34 row_bcast:15 row_mask:0xa bank_mask:0xf
	v_fmac_f32_e32 v2, v110, v110
	v_add_f32_dpp v101, v101, v101 row_shr:4 row_mask:0xf bank_mask:0xf bound_ctrl:1
	s_nop 0
	v_add_f32_dpp v2, v2, v2 quad_perm:[2,3,0,1] row_mask:0xf bank_mask:0xf bound_ctrl:1
	v_add_f32_dpp v32, v32, v32 quad_perm:[2,3,0,1] row_mask:0xf bank_mask:0xf bound_ctrl:1
	v_add_f32_dpp v115, v101, v101 row_shr:8 row_mask:0xf bank_mask:0xf bound_ctrl:1
	v_add_f32_dpp v101, v102, v102 row_bcast:15 row_mask:0xa bank_mask:0xf
	v_add_f32_dpp v2, v2, v2 row_shr:4 row_mask:0xf bank_mask:0xf bound_ctrl:1
	v_add_f32_dpp v32, v32, v32 row_shr:4 row_mask:0xf bank_mask:0xf bound_ctrl:1
	s_nop 0
	v_add_f32_dpp v2, v2, v2 row_shr:8 row_mask:0xf bank_mask:0xf bound_ctrl:1
	v_add_f32_dpp v109, v32, v32 row_shr:8 row_mask:0xf bank_mask:0xf bound_ctrl:1
	v_add_f32_dpp v32, v108, v108 row_bcast:15 row_mask:0xa bank_mask:0xf
	v_fmac_f32_e32 v31, v112, v112
	v_add_f32_dpp v107, v107, v107 row_shr:4 row_mask:0xf bank_mask:0xf bound_ctrl:1
	s_nop 0
	v_add_f32_dpp v31, v31, v31 quad_perm:[2,3,0,1] row_mask:0xf bank_mask:0xf bound_ctrl:1
	v_add_f32_dpp v107, v107, v107 row_shr:8 row_mask:0xf bank_mask:0xf bound_ctrl:1
	v_add_f32_dpp v29, v2, v2 row_bcast:15 row_mask:0xa bank_mask:0xf
	v_add_f32_dpp v31, v31, v31 row_shr:4 row_mask:0xf bank_mask:0xf bound_ctrl:1
	v_add_f32_dpp v19, v19, v19 quad_perm:[2,3,0,1] row_mask:0xf bank_mask:0xf bound_ctrl:1
	s_nop 0
	v_add_f32_dpp v31, v31, v31 row_shr:8 row_mask:0xf bank_mask:0xf bound_ctrl:1
	v_add_f32_dpp v18, v107, v107 row_bcast:15 row_mask:0xa bank_mask:0xf
	v_add_f32_dpp v19, v19, v19 row_shr:4 row_mask:0xf bank_mask:0xf bound_ctrl:1
	v_mul_f32_e32 v117, v89, v9
	s_nop 0
	v_add_f32_dpp v19, v19, v19 row_shr:8 row_mask:0xf bank_mask:0xf bound_ctrl:1
	v_add_f32_dpp v2, v31, v31 row_bcast:15 row_mask:0xa bank_mask:0xf
	v_fmac_f32_e32 v33, v86, v103
	v_mul_f32_e32 v118, v86, v117
	s_nop 0
	v_add_f32_dpp v33, v33, v33 quad_perm:[2,3,0,1] row_mask:0xf bank_mask:0xf bound_ctrl:1
	v_add_f32_dpp v34, v19, v19 row_bcast:15 row_mask:0xa bank_mask:0xf
	s_nop 0
	v_add_f32_dpp v33, v33, v33 row_shr:4 row_mask:0xf bank_mask:0xf bound_ctrl:1
	v_add_f32_dpp v103, v118, v118 quad_perm:[1,0,3,2] row_mask:0xf bank_mask:0xf
	v_add_f32_dpp v35, v35, v35 quad_perm:[2,3,0,1] row_mask:0xf bank_mask:0xf bound_ctrl:1
	v_add_f32_dpp v33, v33, v33 row_shr:8 row_mask:0xf bank_mask:0xf bound_ctrl:1
	v_add_f32_dpp v117, v109, v109 row_bcast:15 row_mask:0xa bank_mask:0xf
	v_add_f32_dpp v35, v35, v35 row_shr:4 row_mask:0xf bank_mask:0xf bound_ctrl:1
	v_add_f32_dpp v30, v30, v30 quad_perm:[2,3,0,1] row_mask:0xf bank_mask:0xf bound_ctrl:1
	s_nop 0
	v_add_f32_dpp v35, v35, v35 row_shr:8 row_mask:0xf bank_mask:0xf bound_ctrl:1
	v_add_f32_dpp v114, v33, v33 row_bcast:15 row_mask:0xa bank_mask:0xf
	v_add_f32_dpp v30, v30, v30 row_shr:4 row_mask:0xf bank_mask:0xf bound_ctrl:1
	s_ashr_i32 s0, s44, 11
	v_add_f32_dpp v107, v35, v35 row_bcast:15 row_mask:0xa bank_mask:0xf
	v_add_f32_dpp v30, v30, v30 row_shr:8 row_mask:0xf bank_mask:0xf bound_ctrl:1
	s_lshl_b32 s4, s44, 6
	v_add_f32_dpp v102, v115, v115 row_bcast:15 row_mask:0xa bank_mask:0xf
	v_add_f32_dpp v103, v103, v103 quad_perm:[2,3,0,1] row_mask:0xf bank_mask:0xf bound_ctrl:1
	s_ashr_i32 s1, s0, 31
	v_add_f32_dpp v33, v30, v30 row_bcast:15 row_mask:0xa bank_mask:0xf
	s_and_b32 s4, s4, 0x1fc0
	v_add_f32_dpp v103, v103, v103 row_shr:4 row_mask:0xf bank_mask:0xf bound_ctrl:1
	s_lshl_b64 s[0:1], s[0:1], 13
	s_nop 0
	v_add_f32_dpp v103, v103, v103 row_shr:8 row_mask:0xf bank_mask:0xf bound_ctrl:1
	v_add_f32_dpp v30, v116, v116 row_bcast:15 row_mask:0xa bank_mask:0xf
	s_add_i32 s4, s4, s33
	s_add_u32 s0, s0, s4
	v_add_f32_dpp v19, v103, v103 row_bcast:15 row_mask:0xa bank_mask:0xf
	s_addc_u32 s1, s1, 0
	s_lshr_b32 s4, s44, 5
	s_and_b32 s4, s4, 60
	v_readlane_b32 s6, v233, 36
	v_mov_b32_e32 v28, v23
	v_add_f32_dpp v123, v105, v105 row_bcast:31 row_mask:0xc bank_mask:0xf
	v_mov_b32_e32 v121, 0
	v_mov_b32_e32 v119, 0
	v_mov_b32_e32 v116, 0
	v_mov_b32_e32 v109, 0
	v_mov_b32_e32 v105, 0
	v_mov_b32_e32 v35, 0
	v_mov_b32_e32 v31, 0
	v_add_f32_dpp v126, v34, v34 row_bcast:31 row_mask:0xc bank_mask:0xf
	v_mov_b32_e32 v122, 0
	v_mov_b32_e32 v120, 0
	v_mov_b32_e32 v118, 0
	v_mov_b32_e32 v115, 0
	v_mov_b32_e32 v108, 0
	v_mov_b32_e32 v103, 0
	v_mov_b32_e32 v34, 0
	v_readlane_b32 s7, v233, 37
	s_add_u32 s22, s6, s4
	v_mov_b32_dpp v121, v113 row_bcast:31 row_mask:0xc bank_mask:0xf
	v_mov_b32_dpp v119, v106 row_bcast:31 row_mask:0xc bank_mask:0xf
	v_mov_b32_dpp v116, v101 row_bcast:31 row_mask:0xc bank_mask:0xf
	v_mov_b32_dpp v109, v32 row_bcast:31 row_mask:0xc bank_mask:0xf
	v_mov_b32_dpp v105, v29 row_bcast:31 row_mask:0xc bank_mask:0xf
	v_mov_b32_dpp v35, v18 row_bcast:31 row_mask:0xc bank_mask:0xf
	v_mov_b32_dpp v31, v2 row_bcast:31 row_mask:0xc bank_mask:0xf
	v_mov_b32_dpp v122, v117 row_bcast:31 row_mask:0xc bank_mask:0xf
	v_mov_b32_dpp v120, v114 row_bcast:31 row_mask:0xc bank_mask:0xf
	v_mov_b32_dpp v118, v107 row_bcast:31 row_mask:0xc bank_mask:0xf
	v_mov_b32_dpp v115, v102 row_bcast:31 row_mask:0xc bank_mask:0xf
	v_mov_b32_dpp v108, v33 row_bcast:31 row_mask:0xc bank_mask:0xf
	v_mov_b32_dpp v103, v30 row_bcast:31 row_mask:0xc bank_mask:0xf
	v_mov_b32_dpp v34, v19 row_bcast:31 row_mask:0xc bank_mask:0xf
	v_cmp_eq_u32_e32 vcc, 0, v28
	s_addc_u32 s23, s7, 0
	v_readlane_b32 s6, v123, 63
	v_readlane_b32 s7, v126, 63
	s_and_saveexec_b64 s[4:5], vcc
	s_cbranch_execz .LBB0_682
	s_lshl_b64 s[8:9], s[0:1], 6
	s_add_u32 s8, s22, s8
	s_addc_u32 s9, s23, s9
	v_mov_b32_e32 v123, s7
	global_store_dword v3, v123, s[8:9]
